# v14_hyz
# speedup vs baseline: 1.0045x; 1.0045x over previous
; #define LAS __attribute__((address_space(3)))
; __device__ __forceinline__ float bf2f(u16 b) { return __uint_as_float(((unsigned)b) << 16); }
; __device__ __forceinline__ float bflo(unsigned w) { return __uint_as_float(w << 16); }
; __device__ __forceinline__ float bfhi(unsigned w) { return __uint_as_float(w & 0xffff0000u); }
; __device__ __forceinline__ unsigned pk2(float lo, float hi) { unsigned r; asm("v_cvt_pk_bf16_f32 %0, %1, %2" : "=v"(r) : "v"(lo), "v"(hi)); return r; }
; __device__ __forceinline__ void phase_hyena(const Params& p, int l, LAS unsigned char* lds, int bid, int G, int tid) {
;     ...
;         for (int ch = ht; ch < 2048; ch += 256) {
;             const int i0 = ch * 8; const u32x4 xr = *(const u32x4*)(x1 + i0), vr = *(const u32x4*)(hv + i0);
;             float xa[10], va[10];
;             xa[1] = bflo(xr.x); xa[2] = bfhi(xr.x); xa[3] = bflo(xr.y); xa[4] = bfhi(xr.y); xa[5] = bflo(xr.z); xa[6] = bfhi(xr.z); xa[7] = bflo(xr.w); xa[8] = bfhi(xr.w);
;             va[1] = bflo(vr.x); va[2] = bfhi(vr.x); va[3] = bflo(vr.y); va[4] = bfhi(vr.y); va[5] = bflo(vr.z); va[6] = bfhi(vr.z); va[7] = bflo(vr.w); va[8] = bfhi(vr.w);
;             const int pl = i0 & (L - 1);
;             if (pl == 0) { xa[0] = 0.f; va[0] = 0.f; } else { xa[0] = bf2f(x1[i0 - 1]); va[0] = bf2f(hv[i0 - 1]); }
;             if (pl + 8 == L) { xa[9] = 0.f; va[9] = 0.f; } else { xa[9] = bf2f(x1[i0 + 8]); va[9] = bf2f(hv[i0 + 8]); }
;             unsigned w[4];
; #pragma unroll
;             for (int j = 0; j < 4; ++j) { float z2[2];
; #pragma unroll
;                 for (int hh = 0; hh < 2; ++hh) { const int e = 2 * j + hh + 1; z2[hh] = (a0 * xa[e - 1] + a1 * xa[e] + a2 * xa[e + 1] + ab) * (v0 * va[e - 1] + v1 * va[e] + v2 * va[e + 1] + vb); }
;                 w[j] = pk2(z2[0], z2[1]); }
;             u32x4 v; v.x = w[0]; v.y = w[1]; v.z = w[2]; v.w = w[3];
;             *(LAS u32x4*)(zl + (i0 >> 8) * 264 + (i0 & 255)) = v;
;         }
.Lhy_z_body:
	v_mov_b32_e32 v41, v1
	s_waitcnt vmcnt(0)
	v_lshlrev_b32_e32 v34, 16, v12
	v_pk_mul_f32 v[40:41], v[32:33], v[40:41]
	v_mov_b32_e32 v35, v10
	v_and_b32_e32 v12, 0xffff0000, v12
	v_lshlrev_b32_e32 v36, 16, v13
	v_and_b32_e32 v44, 0xffff0000, v13
	v_pk_fma_f32 v[40:41], v[30:31], v[34:35], v[40:41]
	v_mov_b32_e32 v13, v2
	v_pk_fma_f32 v[40:41], v[24:25], v[12:13], v[40:41]
	v_mov_b32_e32 v35, v1
	v_pk_add_f32 v[40:41], v[18:19], v[40:41]
	v_mov_b32_e32 v37, v3
	v_mul_f32_e32 v10, v40, v41
	v_pk_mul_f32 v[40:41], v[22:23], v[12:13]
	v_mov_b32_e32 v45, v4
	v_pk_fma_f32 v[34:35], v[20:21], v[34:35], v[40:41]
	v_lshlrev_b32_e32 v46, 16, v14
	v_pk_fma_f32 v[2:3], v[24:25], v[36:37], v[34:35]
	v_pk_mul_f32 v[34:35], v[22:23], v[36:37]
	v_pk_add_f32 v[2:3], v[18:19], v[2:3]
	v_pk_fma_f32 v[12:13], v[20:21], v[12:13], v[34:35]
	v_mul_f32_e32 v1, v2, v3
	v_pk_fma_f32 v[12:13], v[24:25], v[44:45], v[12:13]
	v_cvt_pk_bf16_f32 v2, v10, v1
	v_mov_b32_e32 v47, v5
	v_pk_add_f32 v[12:13], v[18:19], v[12:13]
	v_and_b32_e32 v14, 0xffff0000, v14
	v_mul_f32_e32 v1, v12, v13
	v_pk_mul_f32 v[12:13], v[22:23], v[44:45]
	v_lshlrev_b32_e32 v48, 16, v15
	v_pk_fma_f32 v[12:13], v[20:21], v[36:37], v[12:13]
	v_and_b32_e32 v50, 0xffff0000, v15
	v_pk_fma_f32 v[4:5], v[24:25], v[46:47], v[12:13]
	v_mov_b32_e32 v15, v6
	v_pk_add_f32 v[4:5], v[18:19], v[4:5]
	v_mov_b32_e32 v49, v7
	v_mul_f32_e32 v3, v4, v5
	v_pk_mul_f32 v[4:5], v[22:23], v[46:47]
	v_cvt_pk_bf16_f32 v3, v1, v3
	v_pk_mul_f32 v[6:7], v[22:23], v[48:49]
	v_pk_fma_f32 v[4:5], v[20:21], v[44:45], v[4:5]
	v_pk_fma_f32 v[6:7], v[20:21], v[14:15], v[6:7]
	v_pk_fma_f32 v[4:5], v[24:25], v[14:15], v[4:5]
	v_mov_b32_e32 v51, v8
	v_pk_add_f32 v[4:5], v[18:19], v[4:5]
	v_pk_fma_f32 v[6:7], v[24:25], v[50:51], v[6:7]
	v_mul_f32_e32 v1, v4, v5
	v_pk_mul_f32 v[4:5], v[22:23], v[14:15]
	v_pk_add_f32 v[6:7], v[18:19], v[6:7]
	v_pk_fma_f32 v[4:5], v[20:21], v[46:47], v[4:5]
	v_mov_b32_e32 v39, v9
	v_pk_fma_f32 v[4:5], v[24:25], v[48:49], v[4:5]
	v_add_u32_e32 v42, 0x100, v42
	v_pk_add_f32 v[4:5], v[18:19], v[4:5]
	v_cmp_lt_u32_e32 vcc, s80, v42
	v_mul_f32_e32 v4, v4, v5
	v_cvt_pk_bf16_f32 v4, v1, v4
	v_mul_f32_e32 v1, v6, v7
	v_pk_mul_f32 v[6:7], v[22:23], v[50:51]
	v_lshl_add_u64 v[26:27], v[26:27], 0, s[38:39]
	v_pk_fma_f32 v[6:7], v[20:21], v[48:49], v[6:7]
	v_lshl_add_u64 v[28:29], v[28:29], 0, s[38:39]
	v_pk_fma_f32 v[6:7], v[24:25], v[38:39], v[6:7]
	s_or_b64 s[4:5], vcc, s[4:5]
	v_pk_add_f32 v[6:7], v[18:19], v[6:7]
	v_add_u32_e32 v11, 0x800, v11
	v_mul_f32_e32 v5, v6, v7
	v_cvt_pk_bf16_f32 v5, v1, v5
	ds_write_b128 v17, v[2:5]
	v_add_u32_e32 v17, 0x1080, v17
	s_andn2_b64 exec, exec, s[4:5]
	s_cbranch_execz .LBB0_171
.LBB0_163:
	v_lshl_add_u64 v[36:37], v[28:29], 0, s[14:15]
	v_add_co_u32_e32 v224, vcc, 0x18000000, v36
	v_lshl_add_u64 v[34:35], v[26:27], 0, s[14:15]
	s_nop 0
	v_addc_co_u32_e32 v225, vcc, 0, v37, vcc
	global_load_dwordx4 v[38:41], v[224:225], off
	v_add_co_u32_e32 v226, vcc, 0x18000000, v34
	v_and_b32_e32 v9, s13, v11
	s_nop 0
	v_addc_co_u32_e32 v227, vcc, 0, v35, vcc
	global_load_dwordx4 v[12:15], v[226:227], off
	global_load_ushort v220, v[224:225], off offset:-2
	global_load_ushort v221, v[226:227], off offset:-2
	global_load_ushort v222, v[224:225], off offset:16
	global_load_ushort v223, v[226:227], off offset:16
	v_cmp_ne_u32_e64 s[10:11], 0, v9
	v_cmp_ne_u32_e32 vcc, s18, v9
	s_waitcnt vmcnt(5)
	v_lshlrev_b32_e32 v1, 16, v38
	v_and_b32_e32 v2, 0xffff0000, v38
	v_lshlrev_b32_e32 v3, 16, v39
	v_and_b32_e32 v4, 0xffff0000, v39
	v_lshlrev_b32_e32 v5, 16, v40
	v_and_b32_e32 v6, 0xffff0000, v40
	v_lshlrev_b32_e32 v7, 16, v41
	v_and_b32_e32 v8, 0xffff0000, v41
	s_waitcnt vmcnt(0)
	v_lshlrev_b32_e32 v220, 16, v220
	v_lshlrev_b32_e32 v221, 16, v221
	v_lshlrev_b32_e32 v222, 16, v222
	v_lshlrev_b32_e32 v223, 16, v223
	v_cndmask_b32_e64 v10, 0, v220, s[10:11]
	v_cndmask_b32_e64 v40, 0, v221, s[10:11]
	v_cndmask_b32_e32 v9, 0, v222, vcc
	v_cndmask_b32_e32 v38, 0, v223, vcc
	s_branch .Lhy_z_body
